# down-proj GEMM tile order changed to M-major rounds (16 M-blocks x 16 N-blocks per round, 4x8 per XCD) so the 361 MB activation operand streams from HBM once instead of four times
# speedup vs baseline: 1.0065x; 1.0065x over previous
;     DI bool next(int i, Unit& u) const {
;         if (split == 2) { const long L4 = (long)i * G + c; if (L4 >= 4L * nM) return false; u.pm = (int)(L4 >> 2); u.pn = 0; u.half = (int)(L4 & 3); return true; }
;         u.half = split ? (i & 1) : 1; if (split) i >>= 1;
;         const long L = (long)i * G + c; if (L >= nwg) return false;
;         int wgid = (int)L; { const int q = nwg / NXCD, r = nwg % NXCD, xcd = wgid % NXCD, off = wgid / NXCD; wgid = (xcd < r ? xcd * (q + 1) : r * (q + 1) + (xcd - r) * q) + off; }
;         const int nig = WGM * nN, gid = wgid / nig, fm = gid * WGM, gsz = (nM - fm) < WGM ? (nM - fm) : WGM;
;         u.pm = fm + ((wgid % nig) % gsz); u.pn = (wgid % nig) / gsz; return true;
; __global__ void __launch_bounds__(512, 2) mk_fwd(Params prm) {
;     ...
;     if (IN(8)) { LOADP();
;         for (int _r = 0; _r < NREP(8); ++_r) {
;         pg8::Gemm g{(const bf16_t*)(ws + WS_ACT), (const bf16_t*)(ws + WS_WDN), T, D, DFF, DFF, DFF}; pg8::StaticOrder So; So.init(T, D, G, cid);
.LBB0_791:
	s_cmp_gt_i32 s48, 8
	s_cselect_b64 s[4:5], -1, 0
	s_cmp_lt_i32 s49, 9
	s_cselect_b64 s[6:7], -1, 0
	s_or_b64 s[4:5], s[4:5], s[6:7]
	s_and_b64 vcc, exec, s[4:5]
	s_cbranch_vccnz .LBB0_892
	s_waitcnt lgkmcnt(0)
	s_load_dwordx2 s[36:37], s[0:1], 0xb0
	s_cmpk_lt_i32 s2, 0x400
	v_mov_b32_e32 v8, v180
	s_cselect_b64 s[4:5], -1, 0
	s_cmpk_gt_i32 s2, 0x3ff
	s_movk_i32 s7, 0x2b00
	v_readfirstlane_b32 s6, v8
	s_cbranch_scc1 .LBB0_795
	s_ashr_i32 s8, s2, 31
	s_lshr_b32 s8, s8, 29
	s_add_i32 s8, s2, s8
	s_and_b32 s9, s8, -8
	s_sub_i32 s9, s2, s9
	s_lshl_b32 s11, s9, 7
	s_ashr_i32 s8, s8, 3
	s_mul_i32 s10, s9, 0x81
	s_cmp_lt_i32 s9, 0
	s_cselect_b32 s9, s10, s11
	s_add_i32 s8, s9, s8
	s_ashr_i32 s9, s8, 31
	s_lshr_b32 s9, s9, 25
	s_add_i32 s9, s8, s9
	s_ashr_i32 s10, s9, 7
	s_and_b32 s9, s9, 0xffffff80
	s_sub_i32 s8, s8, s9
	s_bfe_i32 s9, s8, 0x80000
	s_bfe_u32 s9, s9, 0x3000c
	s_add_i32 s9, s8, s9
	s_bfe_i32 s11, s9, 0x80000
	s_and_b32 s9, s9, 0xf8
	s_sub_i32 s8, s8, s9
	s_lshl_b32 s10, s10, 3
	s_sext_i32_i16 s11, s11
	s_sext_i32_i8 s8, s8
	s_add_i32 s60, s10, s8
	s_ashr_i32 s59, s11, 3
	s_cmp_eq_u32 s3, 0x100
	s_cbranch_scc0 .Lr8_skip1
	s_and_b32 s92, s2, 7
	s_lshr_b32 s93, s2, 3
	s_lshr_b32 s94, s92, 1
	s_lshl_b32 s94, s94, 2
	s_and_b32 s95, s93, 3
	s_add_i32 s60, s94, s95
	s_and_b32 s94, s92, 1
	s_lshl_b32 s94, s94, 3
	s_lshr_b32 s95, s93, 2
	s_add_i32 s59, s94, s95
.Lr8_skip1:
	s_andn2_b64 vcc, exec, s[4:5]
	s_cbranch_vccz .LBB0_796

;     DI bool next(int i, Unit& u) const {
;         if (split == 2) { const long L4 = (long)i * G + c; if (L4 >= 4L * nM) return false; u.pm = (int)(L4 >> 2); u.pn = 0; u.half = (int)(L4 & 3); return true; }
;         u.half = split ? (i & 1) : 1; if (split) i >>= 1;
;         const long L = (long)i * G + c; if (L >= nwg) return false;
;         int wgid = (int)L; { const int q = nwg / NXCD, r = nwg % NXCD, xcd = wgid % NXCD, off = wgid / NXCD; wgid = (xcd < r ? xcd * (q + 1) : r * (q + 1) + (xcd - r) * q) + off; }
;         const int nig = WGM * nN, gid = wgid / nig, fm = gid * WGM, gsz = (nM - fm) < WGM ? (nM - fm) : WGM;
;         u.pm = fm + ((wgid % nig) % gsz); u.pn = (wgid % nig) / gsz; return true;
; template <class Epi>
; DI void gemm_phase(LAS unsigned char* lds, const Gemm g, const StaticOrder& S, const Epi& E) {
;     ...
;         const bool has_next = S.next(ui + 1, nxt);
;         const char* nA = has_next ? (const char*)g.A + (size_t)nxt.pm * tstepA + PG8_KOFF(nxt) : cA; const char* nB = has_next ? (const char*)g.Bt + (size_t)nxt.pn * tstepB + PG8_KOFF(nxt) : cB;
.LBB0_807:
	s_cmp_eq_u32 s3, 0x100
	s_cbranch_scc0 .Lr8_skip2
	s_and_b32 s92, s2, 7
	s_lshr_b32 s93, s2, 3
	s_lshr_b32 s94, s92, 1
	s_lshl_b32 s94, s94, 2
	s_and_b32 s95, s93, 3
	s_add_i32 s94, s94, s95
	s_lshl_b32 s95, s46, 4
	s_add_i32 s58, s94, s95
	s_and_b32 s94, s92, 1
	s_lshl_b32 s94, s94, 3
	s_lshr_b32 s95, s93, 2
	s_add_i32 s57, s94, s95

; DI float bflo(unsigned u) { return __uint_as_float(u << 16); }
; DI float bfhi(unsigned u) { return __uint_as_float(u & 0xffff0000u); }
; DI float sigmoidf_(float v) { return fast_rcp(1.0f + fast_exp2(-v * LOG2E)); }
;     DI void operator()(AccRef acc, const Unit& u, int wr, int wc, int fr, int fq) const {
;     ...
;         for (int ai = 0; ai < 2; ++ai) {
;             u32x4 pv[4][2], xv[4][2];
; #pragma unroll
;             for (int m = 0; m < 4; ++m)
; #pragma unroll
;                 for (int bj = 0; bj < 2; ++bj) { const size_t o = (size_t)(row0 + ai * 128 + m * 16) * D + col0 + bj * 128; pv[m][bj] = *(const u32x4*)(pp + o); xv[m][bj] = *(const u32x4*)(x2b + o); }
; #pragma unroll
;             for (int m = 0; m < 4; ++m)
; #pragma unroll
;                 for (int bj = 0; bj < 2; ++bj) {
;                     float* op = out + (size_t)(row0 + ai * 128 + m * 16) * D + col0 + bj * 128;
;                     const u32x4 p4 = pv[m][bj], x4 = xv[m][bj];
;                     const f32x4 a0 = acc[ai][bj][m][0], a1 = acc[ai][bj][m][1];
;                     f32x4 x0, x1;
;                     x0[0] = bflo(x4.x) + sigmoidf_(a0[0]) * bflo(p4.x); x0[1] = bfhi(x4.x) + sigmoidf_(a0[1]) * bfhi(p4.x);
;                     x0[2] = bflo(x4.y) + sigmoidf_(a0[2]) * bflo(p4.y); x0[3] = bfhi(x4.y) + sigmoidf_(a0[3]) * bfhi(p4.y);
;                     x1[0] = bflo(x4.z) + sigmoidf_(a1[0]) * bflo(p4.z); x1[1] = bfhi(x4.z) + sigmoidf_(a1[1]) * bfhi(p4.z);
;                     x1[2] = bflo(x4.w) + sigmoidf_(a1[2]) * bflo(p4.w); x1[3] = bfhi(x4.w) + sigmoidf_(a1[3]) * bfhi(p4.w);
.LBB0_975:
	v_lshl_add_u32 v192, s26, 8, v198
	v_lshl_or_b32 v190, s50, 8, v200
	v_ashrrev_i32_e32 v193, 31, v192
	v_ashrrev_i32_e32 v191, 31, v190
	v_lshlrev_b64 v[128:129], 12, v[192:193]
	v_lshl_add_u64 v[128:129], v[128:129], 0, v[190:191]
	v_lshlrev_b64 v[128:129], 1, v[128:129]
	v_lshl_add_u64 v[130:131], s[8:9], 0, v[128:129]
	global_load_dwordx4 v[204:207], v[130:131], off
	v_lshl_add_u64 v[130:131], s[6:7], 0, v[128:129]
	v_or_b32_e32 v224, 16, v192
	v_or_b32_e32 v196, 32, v192
	v_or_b32_e32 v194, 48, v192
	global_load_dwordx4 v[208:211], v[130:131], off
	v_mul_f32_e32 v124, 0xbfb8aa3b, v124
	v_mul_f32_e32 v125, 0xbfb8aa3b, v125
	v_mul_f32_e32 v126, 0xbfb8aa3b, v126
	v_mul_f32_e32 v127, 0xbfb8aa3b, v127
	v_ashrrev_i32_e32 v225, 31, v224
	v_ashrrev_i32_e32 v197, 31, v196
	v_ashrrev_i32_e32 v195, 31, v194
	v_exp_f32_e32 v134, v124
	v_exp_f32_e32 v135, v125
	v_exp_f32_e32 v136, v126
	v_exp_f32_e32 v137, v127
	v_lshlrev_b64 v[124:125], 14, v[192:193]
	v_lshlrev_b64 v[126:127], 12, v[224:225]
	v_lshlrev_b64 v[130:131], 12, v[196:197]
	v_lshlrev_b64 v[132:133], 12, v[194:195]
	v_lshlrev_b64 v[188:189], 2, v[190:191]
	v_lshl_add_u64 v[124:125], s[4:5], 0, v[124:125]
	v_lshl_add_u64 v[126:127], v[126:127], 0, v[190:191]
	v_lshl_add_u64 v[130:131], v[130:131], 0, v[190:191]
	v_lshl_add_u64 v[132:133], v[132:133], 0, v[190:191]
	v_or_b32_e32 v128, 0x100, v128
	v_lshl_add_u64 v[226:227], v[124:125], 0, v[188:189]
	v_lshlrev_b64 v[124:125], 1, v[126:127]
	v_lshlrev_b64 v[126:127], 1, v[130:131]
	v_lshlrev_b64 v[130:131], 1, v[132:133]
	v_lshl_add_u64 v[132:133], s[6:7], 0, v[128:129]
	v_lshl_add_u64 v[128:129], s[8:9], 0, v[128:129]
	global_load_dwordx4 v[212:215], v[132:133], off
	global_load_dwordx4 v[216:219], v[128:129], off
	v_lshl_add_u64 v[128:129], s[6:7], 0, v[124:125]
	v_lshl_add_u64 v[132:133], s[8:9], 0, v[124:125]
	global_load_dwordx4 v[164:167], v[128:129], off
	global_load_dwordx4 v[168:171], v[132:133], off
	v_add_f32_e32 v142, 1.0, v134
	v_add_f32_e32 v143, 1.0, v135
	v_add_f32_e32 v144, 1.0, v136
	v_add_f32_e32 v145, 1.0, v137
	v_or_b32_e32 v124, 0x100, v124
	v_lshl_add_u64 v[134:135], s[6:7], 0, v[126:127]
	v_lshl_add_u64 v[136:137], s[8:9], 0, v[126:127]
	v_or_b32_e32 v126, 0x100, v126
	v_lshl_add_u64 v[138:139], s[6:7], 0, v[130:131]
	v_lshl_add_u64 v[140:141], s[8:9], 0, v[130:131]
	v_or_b32_e32 v130, 0x100, v130
	v_rcp_f32_e32 v220, v142
	v_rcp_f32_e32 v221, v143
	v_lshl_add_u64 v[128:129], s[6:7], 0, v[124:125]
	v_lshl_add_u64 v[124:125], s[8:9], 0, v[124:125]
	v_lshl_add_u64 v[142:143], s[6:7], 0, v[126:127]
	v_lshl_add_u64 v[126:127], s[8:9], 0, v[126:127]
	v_lshl_add_u64 v[228:229], s[6:7], 0, v[130:131]
	v_lshl_add_u64 v[130:131], s[8:9], 0, v[130:131]
	v_rcp_f32_e32 v222, v144
	v_rcp_f32_e32 v223, v145
	global_load_dwordx4 v[148:151], v[134:135], off
	global_load_dwordx4 v[152:155], v[136:137], off
	s_nop 0
	global_load_dwordx4 v[132:135], v[138:139], off
	s_nop 0
	global_load_dwordx4 v[136:139], v[140:141], off
	global_load_dwordx4 v[156:159], v[128:129], off
	global_load_dwordx4 v[160:163], v[124:125], off
	s_nop 0
	global_load_dwordx4 v[140:143], v[142:143], off
	s_nop 0
	global_load_dwordx4 v[144:147], v[126:127], off
	s_nop 0
	global_load_dwordx4 v[124:127], v[228:229], off
	s_nop 0
	global_load_dwordx4 v[128:131], v[130:131], off
	v_mul_f32_e32 v120, 0xbfb8aa3b, v120
	v_mul_f32_e32 v121, 0xbfb8aa3b, v121
	v_exp_f32_e32 v120, v120
	v_exp_f32_e32 v121, v121
	v_mul_f32_e32 v122, 0xbfb8aa3b, v122
	v_mul_f32_e32 v123, 0xbfb8aa3b, v123
	v_exp_f32_e32 v122, v122
	v_exp_f32_e32 v123, v123
	v_mul_f32_e32 v116, 0xbfb8aa3b, v116
	v_mul_f32_e32 v117, 0xbfb8aa3b, v117
	v_exp_f32_e32 v116, v116
	v_exp_f32_e32 v117, v117
	v_mul_f32_e32 v118, 0xbfb8aa3b, v118
	v_mul_f32_e32 v119, 0xbfb8aa3b, v119
	v_add_f32_e32 v120, 1.0, v120
	v_add_f32_e32 v121, 1.0, v121
	v_exp_f32_e32 v118, v118
	v_exp_f32_e32 v119, v119
	v_mul_f32_e32 v112, 0xbfb8aa3b, v112
	v_mul_f32_e32 v113, 0xbfb8aa3b, v113
	v_rcp_f32_e32 v120, v120
	v_rcp_f32_e32 v121, v121
	v_add_f32_e32 v122, 1.0, v122
	v_add_f32_e32 v123, 1.0, v123
	v_exp_f32_e32 v112, v112
	v_exp_f32_e32 v113, v113
	v_mul_f32_e32 v114, 0xbfb8aa3b, v114
	v_mul_f32_e32 v115, 0xbfb8aa3b, v115
	v_rcp_f32_e32 v122, v122
	v_rcp_f32_e32 v123, v123
	v_exp_f32_e32 v114, v114
	v_exp_f32_e32 v115, v115
	s_waitcnt vmcnt(0)
; DI float bflo(unsigned u) { return __uint_as_float(u << 16); }
; DI float bfhi(unsigned u) { return __uint_as_float(u & 0xffff0000u); }
; DI float sigmoidf_(float v) { return fast_rcp(1.0f + fast_exp2(-v * LOG2E)); }
;     DI void operator()(AccRef acc, const Unit& u, int wr, int wc, int fr, int fq) const {
;     ...
;             for (int m = 0; m < 4; ++m)
; #pragma unroll
;                 for (int bj = 0; bj < 2; ++bj) {
;                     float* op = out + (size_t)(row0 + ai * 128 + m * 16) * D + col0 + bj * 128;
;                     const u32x4 p4 = pv[m][bj], x4 = xv[m][bj];
;                     const f32x4 a0 = acc[ai][bj][m][0], a1 = acc[ai][bj][m][1];
;                     f32x4 x0, x1;
;                     x0[0] = bflo(x4.x) + sigmoidf_(a0[0]) * bflo(p4.x); x0[1] = bfhi(x4.x) + sigmoidf_(a0[1]) * bfhi(p4.x);
;                     x0[2] = bflo(x4.y) + sigmoidf_(a0[2]) * bflo(p4.y); x0[3] = bfhi(x4.y) + sigmoidf_(a0[3]) * bfhi(p4.y);
;                     x1[0] = bflo(x4.z) + sigmoidf_(a1[0]) * bflo(p4.z); x1[1] = bfhi(x4.z) + sigmoidf_(a1[1]) * bfhi(p4.z);
;                     x1[2] = bflo(x4.w) + sigmoidf_(a1[2]) * bflo(p4.w); x1[3] = bfhi(x4.w) + sigmoidf_(a1[3]) * bfhi(p4.w);
;                     *(f32x4*)op = x0; *(f32x4*)(op + 4) = x1;
	v_lshlrev_b32_e32 v228, 16, v204
	v_and_b32_e32 v229, 0xffff0000, v204
	v_lshlrev_b32_e32 v230, 16, v208
	v_and_b32_e32 v231, 0xffff0000, v208
	v_lshlrev_b32_e32 v204, 16, v205
	v_and_b32_e32 v205, 0xffff0000, v205
	v_lshlrev_b32_e32 v208, 16, v209
	v_and_b32_e32 v209, 0xffff0000, v209
	v_add_f32_e32 v116, 1.0, v116
	v_add_f32_e32 v117, 1.0, v117
	v_mul_f32_e32 v108, 0xbfb8aa3b, v108
	v_mul_f32_e32 v109, 0xbfb8aa3b, v109
	v_pk_fma_f32 v[222:223], v[222:223], v[208:209], v[204:205]
	v_lshlrev_b32_e32 v204, 16, v206
	v_and_b32_e32 v205, 0xffff0000, v206
	v_lshlrev_b32_e32 v208, 16, v210
	v_and_b32_e32 v209, 0xffff0000, v210
	v_rcp_f32_e32 v116, v116
	v_rcp_f32_e32 v117, v117
	v_add_f32_e32 v118, 1.0, v118
	v_add_f32_e32 v119, 1.0, v119
	v_exp_f32_e32 v108, v108
	v_exp_f32_e32 v109, v109
	v_mul_f32_e32 v110, 0xbfb8aa3b, v110
	v_mul_f32_e32 v111, 0xbfb8aa3b, v111
	v_pk_fma_f32 v[120:121], v[120:121], v[208:209], v[204:205]
	v_lshlrev_b32_e32 v204, 16, v207
	v_and_b32_e32 v205, 0xffff0000, v207
	v_lshlrev_b32_e32 v206, 16, v211
	v_and_b32_e32 v207, 0xffff0000, v211
	v_rcp_f32_e32 v118, v118
	v_rcp_f32_e32 v119, v119
	v_add_f32_e32 v112, 1.0, v112
	v_add_f32_e32 v113, 1.0, v113
	v_exp_f32_e32 v110, v110
	v_exp_f32_e32 v111, v111
	v_mul_f32_e32 v104, 0xbfb8aa3b, v104
	v_mul_f32_e32 v105, 0xbfb8aa3b, v105
	v_pk_fma_f32 v[122:123], v[122:123], v[206:207], v[204:205]
	v_rcp_f32_e32 v112, v112
	v_rcp_f32_e32 v113, v113
	v_add_f32_e32 v114, 1.0, v114
	v_add_f32_e32 v115, 1.0, v115
	v_exp_f32_e32 v104, v104
	v_exp_f32_e32 v105, v105
	v_mul_f32_e32 v106, 0xbfb8aa3b, v106
	v_mul_f32_e32 v107, 0xbfb8aa3b, v107
	global_store_dwordx4 v[226:227], v[120:123], off offset:16
	v_rcp_f32_e32 v114, v114
	v_rcp_f32_e32 v115, v115
	v_lshlrev_b32_e32 v120, 16, v216
	v_and_b32_e32 v121, 0xffff0000, v216
	v_lshlrev_b32_e32 v122, 16, v212
	v_and_b32_e32 v123, 0xffff0000, v212
	v_exp_f32_e32 v106, v106
	v_exp_f32_e32 v107, v107
	v_pk_fma_f32 v[116:117], v[116:117], v[122:123], v[120:121]
	v_lshlrev_b32_e32 v120, 16, v217
	v_and_b32_e32 v121, 0xffff0000, v217
	v_lshlrev_b32_e32 v122, 16, v213
	v_and_b32_e32 v123, 0xffff0000, v213
	v_add_f32_e32 v108, 1.0, v108
	v_add_f32_e32 v109, 1.0, v109
	v_mul_f32_e32 v100, 0xbfb8aa3b, v100
	v_mul_f32_e32 v101, 0xbfb8aa3b, v101
	v_pk_fma_f32 v[118:119], v[118:119], v[122:123], v[120:121]
	v_lshlrev_b32_e32 v120, 16, v218
	v_and_b32_e32 v121, 0xffff0000, v218
	v_lshlrev_b32_e32 v122, 16, v214
	v_and_b32_e32 v123, 0xffff0000, v214
	v_rcp_f32_e32 v108, v108
	v_rcp_f32_e32 v109, v109
	v_add_f32_e32 v110, 1.0, v110
	v_add_f32_e32 v111, 1.0, v111
	v_exp_f32_e32 v100, v100
	v_exp_f32_e32 v101, v101
	v_mul_f32_e32 v102, 0xbfb8aa3b, v102
	v_mul_f32_e32 v103, 0xbfb8aa3b, v103
	v_pk_fma_f32 v[112:113], v[112:113], v[122:123], v[120:121]
	v_lshlrev_b32_e32 v120, 16, v219
	v_and_b32_e32 v121, 0xffff0000, v219
	v_lshlrev_b32_e32 v122, 16, v215
	v_and_b32_e32 v123, 0xffff0000, v215
	v_rcp_f32_e32 v110, v110
	v_rcp_f32_e32 v111, v111
	v_add_f32_e32 v104, 1.0, v104
	v_add_f32_e32 v105, 1.0, v105
	v_exp_f32_e32 v102, v102
	v_exp_f32_e32 v103, v103
	v_mul_f32_e32 v96, 0xbfb8aa3b, v96
	v_mul_f32_e32 v97, 0xbfb8aa3b, v97
	v_pk_fma_f32 v[220:221], v[220:221], v[230:231], v[228:229]
	v_pk_fma_f32 v[114:115], v[114:115], v[122:123], v[120:121]
	v_rcp_f32_e32 v104, v104
	v_rcp_f32_e32 v105, v105
	v_add_f32_e32 v106, 1.0, v106
	v_add_f32_e32 v107, 1.0, v107
	v_exp_f32_e32 v96, v96
	v_exp_f32_e32 v97, v97
	v_mul_f32_e32 v98, 0xbfb8aa3b, v98
	v_mul_f32_e32 v99, 0xbfb8aa3b, v99
	global_store_dwordx4 v[226:227], v[220:223], off
	global_store_dwordx4 v[226:227], v[116:119], off offset:512
	global_store_dwordx4 v[226:227], v[112:115], off offset:528
	v_rcp_f32_e32 v106, v106
	v_lshlrev_b32_e32 v116, 16, v164
	v_lshlrev_b32_e32 v114, 16, v168
	v_and_b32_e32 v115, 0xffff0000, v168
	v_and_b32_e32 v117, 0xffff0000, v164
	v_rcp_f32_e32 v107, v107
	v_exp_f32_e32 v98, v98
	v_exp_f32_e32 v99, v99
	v_pk_fma_f32 v[108:109], v[108:109], v[116:117], v[114:115]
	v_lshlrev_b32_e32 v114, 16, v169
	v_and_b32_e32 v115, 0xffff0000, v169
	v_lshlrev_b32_e32 v116, 16, v165
	v_and_b32_e32 v117, 0xffff0000, v165
	v_add_f32_e32 v100, 1.0, v100
	v_add_f32_e32 v101, 1.0, v101
	v_mul_f32_e32 v92, 0xbfb8aa3b, v92
	v_mul_f32_e32 v93, 0xbfb8aa3b, v93
	v_lshlrev_b64 v[112:113], 14, v[224:225]
	v_pk_fma_f32 v[110:111], v[110:111], v[116:117], v[114:115]
	v_lshlrev_b32_e32 v114, 16, v170
	v_and_b32_e32 v115, 0xffff0000, v170
	v_lshlrev_b32_e32 v116, 16, v166
	v_and_b32_e32 v117, 0xffff0000, v166
	v_rcp_f32_e32 v100, v100
	v_rcp_f32_e32 v101, v101
	v_add_f32_e32 v102, 1.0, v102
	v_add_f32_e32 v103, 1.0, v103
	v_exp_f32_e32 v92, v92
	v_exp_f32_e32 v93, v93
	v_mul_f32_e32 v94, 0xbfb8aa3b, v94
	v_mul_f32_e32 v95, 0xbfb8aa3b, v95
	v_lshl_add_u64 v[112:113], s[4:5], 0, v[112:113]
	v_pk_fma_f32 v[104:105], v[104:105], v[116:117], v[114:115]
	v_lshlrev_b32_e32 v114, 16, v171
	v_and_b32_e32 v115, 0xffff0000, v171
	v_lshlrev_b32_e32 v116, 16, v167
	v_and_b32_e32 v117, 0xffff0000, v167
	v_rcp_f32_e32 v102, v102
	v_rcp_f32_e32 v103, v103
	v_add_f32_e32 v96, 1.0, v96
	v_add_f32_e32 v97, 1.0, v97
	v_exp_f32_e32 v94, v94
	v_exp_f32_e32 v95, v95
	v_mul_f32_e32 v88, 0xbfb8aa3b, v88
	v_mul_f32_e32 v89, 0xbfb8aa3b, v89
	v_lshl_add_u64 v[112:113], v[112:113], 0, v[188:189]
	v_pk_fma_f32 v[106:107], v[106:107], v[116:117], v[114:115]
	v_rcp_f32_e32 v96, v96
	v_rcp_f32_e32 v97, v97
	v_add_f32_e32 v98, 1.0, v98
	v_add_f32_e32 v99, 1.0, v99
	v_exp_f32_e32 v88, v88
	v_exp_f32_e32 v89, v89
	v_mul_f32_e32 v90, 0xbfb8aa3b, v90
	v_mul_f32_e32 v91, 0xbfb8aa3b, v91
	global_store_dwordx4 v[112:113], v[104:107], off offset:16
; DI float bflo(unsigned u) { return __uint_as_float(u << 16); }
; DI float bfhi(unsigned u) { return __uint_as_float(u & 0xffff0000u); }
; DI float sigmoidf_(float v) { return fast_rcp(1.0f + fast_exp2(-v * LOG2E)); }
;     DI void operator()(AccRef acc, const Unit& u, int wr, int wc, int fr, int fq) const {
;     ...
;             for (int m = 0; m < 4; ++m)
; #pragma unroll
;                 for (int bj = 0; bj < 2; ++bj) {
;                     float* op = out + (size_t)(row0 + ai * 128 + m * 16) * D + col0 + bj * 128;
;                     const u32x4 p4 = pv[m][bj], x4 = xv[m][bj];
;                     const f32x4 a0 = acc[ai][bj][m][0], a1 = acc[ai][bj][m][1];
;                     f32x4 x0, x1;
;                     x0[0] = bflo(x4.x) + sigmoidf_(a0[0]) * bflo(p4.x); x0[1] = bfhi(x4.x) + sigmoidf_(a0[1]) * bfhi(p4.x);
;                     x0[2] = bflo(x4.y) + sigmoidf_(a0[2]) * bflo(p4.y); x0[3] = bfhi(x4.y) + sigmoidf_(a0[3]) * bfhi(p4.y);
;                     x1[0] = bflo(x4.z) + sigmoidf_(a1[0]) * bflo(p4.z); x1[1] = bfhi(x4.z) + sigmoidf_(a1[1]) * bfhi(p4.z);
;                     x1[2] = bflo(x4.w) + sigmoidf_(a1[2]) * bflo(p4.w); x1[3] = bfhi(x4.w) + sigmoidf_(a1[3]) * bfhi(p4.w);
;                     *(f32x4*)op = x0; *(f32x4*)(op + 4) = x1;
	v_rcp_f32_e32 v98, v98
	v_rcp_f32_e32 v99, v99
	v_lshlrev_b32_e32 v104, 16, v160
	v_and_b32_e32 v105, 0xffff0000, v160
	v_lshlrev_b32_e32 v106, 16, v156
	v_and_b32_e32 v107, 0xffff0000, v156
	v_exp_f32_e32 v90, v90
	v_exp_f32_e32 v91, v91
	v_pk_fma_f32 v[100:101], v[100:101], v[106:107], v[104:105]
	v_lshlrev_b32_e32 v104, 16, v161
	v_and_b32_e32 v105, 0xffff0000, v161
	v_lshlrev_b32_e32 v106, 16, v157
	v_and_b32_e32 v107, 0xffff0000, v157
	v_add_f32_e32 v92, 1.0, v92
	v_add_f32_e32 v93, 1.0, v93
	v_mul_f32_e32 v84, 0xbfb8aa3b, v84
	v_mul_f32_e32 v85, 0xbfb8aa3b, v85
	v_pk_fma_f32 v[102:103], v[102:103], v[106:107], v[104:105]
	v_lshlrev_b32_e32 v104, 16, v162
	v_and_b32_e32 v105, 0xffff0000, v162
	v_lshlrev_b32_e32 v106, 16, v158
	v_and_b32_e32 v107, 0xffff0000, v158
	v_rcp_f32_e32 v92, v92
	v_rcp_f32_e32 v93, v93
	v_add_f32_e32 v94, 1.0, v94
	v_add_f32_e32 v95, 1.0, v95
	v_exp_f32_e32 v84, v84
	v_exp_f32_e32 v85, v85
	v_mul_f32_e32 v86, 0xbfb8aa3b, v86
	v_mul_f32_e32 v87, 0xbfb8aa3b, v87
	v_pk_fma_f32 v[96:97], v[96:97], v[106:107], v[104:105]
	v_lshlrev_b32_e32 v104, 16, v163
	v_and_b32_e32 v105, 0xffff0000, v163
	v_lshlrev_b32_e32 v106, 16, v159
	v_and_b32_e32 v107, 0xffff0000, v159
	v_rcp_f32_e32 v94, v94
	v_rcp_f32_e32 v95, v95
	v_add_f32_e32 v88, 1.0, v88
	v_add_f32_e32 v89, 1.0, v89
	v_exp_f32_e32 v86, v86
	v_exp_f32_e32 v87, v87
	v_mul_f32_e32 v80, 0xbfb8aa3b, v80
	v_mul_f32_e32 v81, 0xbfb8aa3b, v81
	v_pk_fma_f32 v[98:99], v[98:99], v[106:107], v[104:105]
	v_rcp_f32_e32 v88, v88
	v_rcp_f32_e32 v89, v89
	v_add_f32_e32 v90, 1.0, v90
	v_add_f32_e32 v91, 1.0, v91
	v_exp_f32_e32 v80, v80
	v_exp_f32_e32 v81, v81
	v_mul_f32_e32 v82, 0xbfb8aa3b, v82
	v_mul_f32_e32 v83, 0xbfb8aa3b, v83
	global_store_dwordx4 v[112:113], v[108:111], off
	global_store_dwordx4 v[112:113], v[100:103], off offset:512
	global_store_dwordx4 v[112:113], v[96:99], off offset:528
	v_rcp_f32_e32 v90, v90
	v_lshlrev_b32_e32 v100, 16, v148
	v_lshlrev_b32_e32 v98, 16, v152
	v_and_b32_e32 v99, 0xffff0000, v152
	v_and_b32_e32 v101, 0xffff0000, v148
	v_rcp_f32_e32 v91, v91
	v_exp_f32_e32 v82, v82
	v_exp_f32_e32 v83, v83
	v_pk_fma_f32 v[92:93], v[92:93], v[100:101], v[98:99]
	v_lshlrev_b32_e32 v98, 16, v153
	v_and_b32_e32 v99, 0xffff0000, v153
	v_lshlrev_b32_e32 v100, 16, v149
	v_and_b32_e32 v101, 0xffff0000, v149
	v_add_f32_e32 v84, 1.0, v84
	v_add_f32_e32 v85, 1.0, v85
	v_mul_f32_e32 v76, 0xbfb8aa3b, v76
	v_mul_f32_e32 v77, 0xbfb8aa3b, v77
	v_lshlrev_b64 v[96:97], 14, v[196:197]
	v_pk_fma_f32 v[94:95], v[94:95], v[100:101], v[98:99]
	v_lshlrev_b32_e32 v98, 16, v154
	v_and_b32_e32 v99, 0xffff0000, v154
	v_lshlrev_b32_e32 v100, 16, v150
	v_and_b32_e32 v101, 0xffff0000, v150
	v_rcp_f32_e32 v84, v84
	v_rcp_f32_e32 v85, v85
	v_add_f32_e32 v86, 1.0, v86
	v_add_f32_e32 v87, 1.0, v87
	v_exp_f32_e32 v76, v76
	v_exp_f32_e32 v77, v77
	v_mul_f32_e32 v78, 0xbfb8aa3b, v78
	v_mul_f32_e32 v79, 0xbfb8aa3b, v79
	v_lshl_add_u64 v[96:97], s[4:5], 0, v[96:97]
	v_pk_fma_f32 v[88:89], v[88:89], v[100:101], v[98:99]
	v_lshlrev_b32_e32 v98, 16, v155
	v_and_b32_e32 v99, 0xffff0000, v155
	v_lshlrev_b32_e32 v100, 16, v151
	v_and_b32_e32 v101, 0xffff0000, v151
	v_rcp_f32_e32 v86, v86
	v_rcp_f32_e32 v87, v87
	v_add_f32_e32 v80, 1.0, v80
	v_add_f32_e32 v81, 1.0, v81
	v_exp_f32_e32 v78, v78
	v_exp_f32_e32 v79, v79
	v_mul_f32_e32 v72, 0xbfb8aa3b, v72
	v_mul_f32_e32 v73, 0xbfb8aa3b, v73
	v_lshl_add_u64 v[96:97], v[96:97], 0, v[188:189]
	v_pk_fma_f32 v[90:91], v[90:91], v[100:101], v[98:99]
	v_rcp_f32_e32 v80, v80
	v_rcp_f32_e32 v81, v81
	v_add_f32_e32 v82, 1.0, v82
	v_add_f32_e32 v83, 1.0, v83
	v_exp_f32_e32 v72, v72
	v_exp_f32_e32 v73, v73
	v_mul_f32_e32 v74, 0xbfb8aa3b, v74
	v_mul_f32_e32 v75, 0xbfb8aa3b, v75
	global_store_dwordx4 v[96:97], v[88:91], off offset:16
	v_rcp_f32_e32 v82, v82
	v_rcp_f32_e32 v83, v83
	v_lshlrev_b32_e32 v88, 16, v144
	v_and_b32_e32 v89, 0xffff0000, v144
	v_lshlrev_b32_e32 v90, 16, v140
	v_and_b32_e32 v91, 0xffff0000, v140
	v_exp_f32_e32 v74, v74
	v_exp_f32_e32 v75, v75
	v_pk_fma_f32 v[84:85], v[84:85], v[90:91], v[88:89]
	v_lshlrev_b32_e32 v88, 16, v145
	v_and_b32_e32 v89, 0xffff0000, v145
	v_lshlrev_b32_e32 v90, 16, v141
	v_and_b32_e32 v91, 0xffff0000, v141
	v_add_f32_e32 v76, 1.0, v76
	v_add_f32_e32 v77, 1.0, v77
	v_mul_f32_e32 v68, 0xbfb8aa3b, v68
	v_mul_f32_e32 v69, 0xbfb8aa3b, v69
	v_pk_fma_f32 v[86:87], v[86:87], v[90:91], v[88:89]
	v_lshlrev_b32_e32 v88, 16, v146
	v_and_b32_e32 v89, 0xffff0000, v146
	v_lshlrev_b32_e32 v90, 16, v142
	v_and_b32_e32 v91, 0xffff0000, v142
	v_rcp_f32_e32 v76, v76
	v_rcp_f32_e32 v77, v77
	v_add_f32_e32 v78, 1.0, v78
	v_add_f32_e32 v79, 1.0, v79
	v_exp_f32_e32 v68, v68
	v_exp_f32_e32 v69, v69
	v_mul_f32_e32 v70, 0xbfb8aa3b, v70
	v_mul_f32_e32 v71, 0xbfb8aa3b, v71
	v_pk_fma_f32 v[80:81], v[80:81], v[90:91], v[88:89]
	v_lshlrev_b32_e32 v88, 16, v147
	v_and_b32_e32 v89, 0xffff0000, v147
	v_lshlrev_b32_e32 v90, 16, v143
	v_and_b32_e32 v91, 0xffff0000, v143
	v_rcp_f32_e32 v78, v78
	v_rcp_f32_e32 v79, v79
	v_add_f32_e32 v72, 1.0, v72
	v_add_f32_e32 v73, 1.0, v73
	v_exp_f32_e32 v70, v70
	v_exp_f32_e32 v71, v71
	v_mul_f32_e32 v64, 0xbfb8aa3b, v64
	v_mul_f32_e32 v65, 0xbfb8aa3b, v65
	v_pk_fma_f32 v[82:83], v[82:83], v[90:91], v[88:89]
	v_rcp_f32_e32 v72, v72
	v_rcp_f32_e32 v73, v73
	v_add_f32_e32 v74, 1.0, v74
	v_add_f32_e32 v75, 1.0, v75
	v_exp_f32_e32 v64, v64
	v_exp_f32_e32 v65, v65
	v_mul_f32_e32 v66, 0xbfb8aa3b, v66
	v_mul_f32_e32 v67, 0xbfb8aa3b, v67
	global_store_dwordx4 v[96:97], v[92:95], off
	global_store_dwordx4 v[96:97], v[84:87], off offset:512
	global_store_dwordx4 v[96:97], v[80:83], off offset:528
	v_rcp_f32_e32 v74, v74
; DI float bflo(unsigned u) { return __uint_as_float(u << 16); }
; DI float bfhi(unsigned u) { return __uint_as_float(u & 0xffff0000u); }
; DI float sigmoidf_(float v) { return fast_rcp(1.0f + fast_exp2(-v * LOG2E)); }
;     DI void operator()(AccRef acc, const Unit& u, int wr, int wc, int fr, int fq) const {
;     ...
;         for (int ai = 0; ai < 2; ++ai) {
;             u32x4 pv[4][2], xv[4][2];
; #pragma unroll
;             for (int m = 0; m < 4; ++m)
; #pragma unroll
;                 for (int bj = 0; bj < 2; ++bj) { const size_t o = (size_t)(row0 + ai * 128 + m * 16) * D + col0 + bj * 128; pv[m][bj] = *(const u32x4*)(pp + o); xv[m][bj] = *(const u32x4*)(x2b + o); }
; #pragma unroll
;             for (int m = 0; m < 4; ++m)
; #pragma unroll
;                 for (int bj = 0; bj < 2; ++bj) {
;                     float* op = out + (size_t)(row0 + ai * 128 + m * 16) * D + col0 + bj * 128;
;                     const u32x4 p4 = pv[m][bj], x4 = xv[m][bj];
;                     const f32x4 a0 = acc[ai][bj][m][0], a1 = acc[ai][bj][m][1];
;                     f32x4 x0, x1;
;                     x0[0] = bflo(x4.x) + sigmoidf_(a0[0]) * bflo(p4.x); x0[1] = bfhi(x4.x) + sigmoidf_(a0[1]) * bfhi(p4.x);
;                     x0[2] = bflo(x4.y) + sigmoidf_(a0[2]) * bflo(p4.y); x0[3] = bfhi(x4.y) + sigmoidf_(a0[3]) * bfhi(p4.y);
;                     x1[0] = bflo(x4.z) + sigmoidf_(a1[0]) * bflo(p4.z); x1[1] = bfhi(x4.z) + sigmoidf_(a1[1]) * bfhi(p4.z);
;                     x1[2] = bflo(x4.w) + sigmoidf_(a1[2]) * bflo(p4.w); x1[3] = bfhi(x4.w) + sigmoidf_(a1[3]) * bfhi(p4.w);
;                     *(f32x4*)op = x0; *(f32x4*)(op + 4) = x1;
	v_lshlrev_b32_e32 v84, 16, v132
	v_lshlrev_b32_e32 v82, 16, v136
	v_and_b32_e32 v83, 0xffff0000, v136
	v_and_b32_e32 v85, 0xffff0000, v132
	v_rcp_f32_e32 v75, v75
	v_exp_f32_e32 v66, v66
	v_exp_f32_e32 v67, v67
	v_pk_fma_f32 v[76:77], v[76:77], v[84:85], v[82:83]
	v_lshlrev_b32_e32 v82, 16, v137
	v_and_b32_e32 v83, 0xffff0000, v137
	v_lshlrev_b32_e32 v84, 16, v133
	v_and_b32_e32 v85, 0xffff0000, v133
	v_add_f32_e32 v68, 1.0, v68
	v_add_f32_e32 v69, 1.0, v69
	v_lshlrev_b64 v[80:81], 14, v[194:195]
	v_pk_fma_f32 v[78:79], v[78:79], v[84:85], v[82:83]
	v_lshlrev_b32_e32 v82, 16, v138
	v_and_b32_e32 v83, 0xffff0000, v138
	v_lshlrev_b32_e32 v84, 16, v134
	v_and_b32_e32 v85, 0xffff0000, v134
	v_rcp_f32_e32 v68, v68
	v_rcp_f32_e32 v69, v69
	v_add_f32_e32 v70, 1.0, v70
	v_add_f32_e32 v71, 1.0, v71
	v_lshl_add_u64 v[80:81], s[4:5], 0, v[80:81]
	v_pk_fma_f32 v[72:73], v[72:73], v[84:85], v[82:83]
	v_lshlrev_b32_e32 v82, 16, v139
	v_and_b32_e32 v83, 0xffff0000, v139
	v_lshlrev_b32_e32 v84, 16, v135
	v_and_b32_e32 v85, 0xffff0000, v135
	v_rcp_f32_e32 v70, v70
	v_rcp_f32_e32 v71, v71
	v_add_f32_e32 v64, 1.0, v64
	v_add_f32_e32 v65, 1.0, v65
	v_lshl_add_u64 v[80:81], v[80:81], 0, v[188:189]
	v_pk_fma_f32 v[74:75], v[74:75], v[84:85], v[82:83]
	v_rcp_f32_e32 v64, v64
	v_rcp_f32_e32 v65, v65
	v_add_f32_e32 v66, 1.0, v66
	v_add_f32_e32 v67, 1.0, v67
	global_store_dwordx4 v[80:81], v[72:75], off offset:16
	v_rcp_f32_e32 v66, v66
	v_rcp_f32_e32 v67, v67
	v_lshlrev_b32_e32 v72, 16, v128
	v_and_b32_e32 v73, 0xffff0000, v128
	v_lshlrev_b32_e32 v74, 16, v124
	v_and_b32_e32 v75, 0xffff0000, v124
	v_pk_fma_f32 v[68:69], v[68:69], v[74:75], v[72:73]
	v_lshlrev_b32_e32 v72, 16, v129
	v_and_b32_e32 v73, 0xffff0000, v129
	v_lshlrev_b32_e32 v74, 16, v125
	v_and_b32_e32 v75, 0xffff0000, v125
	v_pk_fma_f32 v[70:71], v[70:71], v[74:75], v[72:73]
	v_lshlrev_b32_e32 v72, 16, v130
	v_and_b32_e32 v73, 0xffff0000, v130
	v_lshlrev_b32_e32 v74, 16, v126
	v_and_b32_e32 v75, 0xffff0000, v126
	v_add_u32_e32 v134, 0x80, v192
	v_pk_fma_f32 v[64:65], v[64:65], v[74:75], v[72:73]
	v_lshlrev_b32_e32 v72, 16, v131
	v_and_b32_e32 v73, 0xffff0000, v131
	v_lshlrev_b32_e32 v74, 16, v127
	v_and_b32_e32 v75, 0xffff0000, v127
	v_ashrrev_i32_e32 v135, 31, v134
	global_store_dwordx4 v[80:81], v[76:79], off
	v_pk_fma_f32 v[66:67], v[66:67], v[74:75], v[72:73]
	global_store_dwordx4 v[80:81], v[68:71], off offset:512
	global_store_dwordx4 v[80:81], v[64:67], off offset:528
	v_add_u32_e32 v116, 0x90, v192
	v_ashrrev_i32_e32 v117, 31, v116
	v_lshlrev_b64 v[64:65], 12, v[134:135]
	v_lshl_add_u64 v[64:65], v[64:65], 0, v[190:191]
	v_lshlrev_b64 v[64:65], 1, v[64:65]
	v_lshl_add_u64 v[66:67], s[8:9], 0, v[64:65]
	global_load_dwordx4 v[118:121], v[66:67], off
	v_lshl_add_u64 v[66:67], s[6:7], 0, v[64:65]
	global_load_dwordx4 v[122:125], v[66:67], off
	v_or_b32_e32 v64, 0x100, v64
	v_lshl_add_u64 v[66:67], s[6:7], 0, v[64:65]
	v_lshl_add_u64 v[64:65], s[8:9], 0, v[64:65]
	global_load_dwordx4 v[126:129], v[66:67], off
	global_load_dwordx4 v[130:133], v[64:65], off
	v_lshlrev_b64 v[64:65], 12, v[116:117]
	v_lshl_add_u64 v[64:65], v[64:65], 0, v[190:191]
	v_lshlrev_b64 v[64:65], 1, v[64:65]
	v_lshl_add_u64 v[66:67], s[6:7], 0, v[64:65]
	v_lshl_add_u64 v[68:69], s[8:9], 0, v[64:65]
	global_load_dwordx4 v[104:107], v[66:67], off
	global_load_dwordx4 v[108:111], v[68:69], off
	v_or_b32_e32 v64, 0x100, v64
	v_lshl_add_u64 v[66:67], s[6:7], 0, v[64:65]
	v_add_u32_e32 v114, 0xa0, v192
	v_lshl_add_u64 v[64:65], s[8:9], 0, v[64:65]
	global_load_dwordx4 v[96:99], v[66:67], off
	global_load_dwordx4 v[100:103], v[64:65], off
	v_ashrrev_i32_e32 v115, 31, v114
	v_lshlrev_b64 v[64:65], 12, v[114:115]
	v_lshl_add_u64 v[64:65], v[64:65], 0, v[190:191]
	v_lshlrev_b64 v[64:65], 1, v[64:65]
	v_lshl_add_u64 v[66:67], s[6:7], 0, v[64:65]
	v_lshl_add_u64 v[68:69], s[8:9], 0, v[64:65]
	global_load_dwordx4 v[88:91], v[66:67], off
	global_load_dwordx4 v[92:95], v[68:69], off
	v_or_b32_e32 v64, 0x100, v64
	v_lshl_add_u64 v[66:67], s[6:7], 0, v[64:65]
	v_add_u32_e32 v112, 0xb0, v192
	v_lshl_add_u64 v[64:65], s[8:9], 0, v[64:65]
	global_load_dwordx4 v[80:83], v[66:67], off
	global_load_dwordx4 v[84:87], v[64:65], off
	v_ashrrev_i32_e32 v113, 31, v112
	v_lshlrev_b64 v[64:65], 12, v[112:113]
	v_lshl_add_u64 v[64:65], v[64:65], 0, v[190:191]
	v_lshlrev_b64 v[64:65], 1, v[64:65]
	v_lshl_add_u64 v[66:67], s[6:7], 0, v[64:65]
	v_lshl_add_u64 v[68:69], s[8:9], 0, v[64:65]
	global_load_dwordx4 v[72:75], v[66:67], off
	global_load_dwordx4 v[76:79], v[68:69], off
	v_or_b32_e32 v64, 0x100, v64
	v_lshl_add_u64 v[66:67], s[6:7], 0, v[64:65]
	v_lshl_add_u64 v[68:69], s[8:9], 0, v[64:65]
	global_load_dwordx4 v[64:67], v[66:67], off
	s_nop 0
	global_load_dwordx4 v[68:71], v[68:69], off
	v_mul_f32_e32 v62, 0xbfb8aa3b, v62
	v_mul_f32_e32 v63, 0xbfb8aa3b, v63
	v_exp_f32_e32 v62, v62
	v_exp_f32_e32 v63, v63
	v_mul_f32_e32 v56, 0xbfb8aa3b, v56
	v_mul_f32_e32 v57, 0xbfb8aa3b, v57
	v_exp_f32_e32 v56, v56
	v_exp_f32_e32 v57, v57
	v_mul_f32_e32 v58, 0xbfb8aa3b, v58
	v_mul_f32_e32 v59, 0xbfb8aa3b, v59
	v_exp_f32_e32 v58, v58
	v_exp_f32_e32 v59, v59
	v_mul_f32_e32 v52, 0xbfb8aa3b, v52
	v_mul_f32_e32 v53, 0xbfb8aa3b, v53
	v_add_f32_e32 v62, 1.0, v62
	v_add_f32_e32 v63, 1.0, v63
	v_exp_f32_e32 v52, v52
	v_exp_f32_e32 v53, v53
	v_mul_f32_e32 v54, 0xbfb8aa3b, v54
	v_mul_f32_e32 v55, 0xbfb8aa3b, v55
	v_rcp_f32_e32 v62, v62
	v_rcp_f32_e32 v63, v63
	v_add_f32_e32 v56, 1.0, v56
	v_add_f32_e32 v57, 1.0, v57
	v_exp_f32_e32 v54, v54
	v_exp_f32_e32 v55, v55
	v_mul_f32_e32 v48, 0xbfb8aa3b, v48
	v_mul_f32_e32 v49, 0xbfb8aa3b, v49
	v_mul_f32_e32 v60, 0xbfb8aa3b, v60
	v_mul_f32_e32 v61, 0xbfb8aa3b, v61
	v_rcp_f32_e32 v56, v56
	v_rcp_f32_e32 v57, v57
	v_add_f32_e32 v58, 1.0, v58
	v_add_f32_e32 v59, 1.0, v59
	v_exp_f32_e32 v48, v48
	v_exp_f32_e32 v49, v49
	v_mul_f32_e32 v50, 0xbfb8aa3b, v50
	v_mul_f32_e32 v51, 0xbfb8aa3b, v51
	v_exp_f32_e32 v60, v60
	v_exp_f32_e32 v61, v61
	v_rcp_f32_e32 v58, v58
	v_rcp_f32_e32 v59, v59
	v_exp_f32_e32 v50, v50
	v_exp_f32_e32 v51, v51
	s_waitcnt vmcnt(0)
; DI float bflo(unsigned u) { return __uint_as_float(u << 16); }
; DI float bfhi(unsigned u) { return __uint_as_float(u & 0xffff0000u); }
; DI float sigmoidf_(float v) { return fast_rcp(1.0f + fast_exp2(-v * LOG2E)); }
;     DI void operator()(AccRef acc, const Unit& u, int wr, int wc, int fr, int fq) const {
;     ...
;             for (int m = 0; m < 4; ++m)
; #pragma unroll
;                 for (int bj = 0; bj < 2; ++bj) {
;                     float* op = out + (size_t)(row0 + ai * 128 + m * 16) * D + col0 + bj * 128;
;                     const u32x4 p4 = pv[m][bj], x4 = xv[m][bj];
;                     const f32x4 a0 = acc[ai][bj][m][0], a1 = acc[ai][bj][m][1];
;                     f32x4 x0, x1;
;                     x0[0] = bflo(x4.x) + sigmoidf_(a0[0]) * bflo(p4.x); x0[1] = bfhi(x4.x) + sigmoidf_(a0[1]) * bfhi(p4.x);
;                     x0[2] = bflo(x4.y) + sigmoidf_(a0[2]) * bflo(p4.y); x0[3] = bfhi(x4.y) + sigmoidf_(a0[3]) * bfhi(p4.y);
;                     x1[0] = bflo(x4.z) + sigmoidf_(a1[0]) * bflo(p4.z); x1[1] = bfhi(x4.z) + sigmoidf_(a1[1]) * bfhi(p4.z);
;                     x1[2] = bflo(x4.w) + sigmoidf_(a1[2]) * bflo(p4.w); x1[3] = bfhi(x4.w) + sigmoidf_(a1[3]) * bfhi(p4.w);
;                     *(f32x4*)op = x0; *(f32x4*)(op + 4) = x1;
	v_lshlrev_b32_e32 v136, 16, v118
	v_and_b32_e32 v137, 0xffff0000, v118
	v_lshlrev_b32_e32 v138, 16, v122
	v_and_b32_e32 v139, 0xffff0000, v122
	v_lshlrev_b32_e32 v118, 16, v119
	v_and_b32_e32 v119, 0xffff0000, v119
	v_lshlrev_b32_e32 v122, 16, v123
	v_and_b32_e32 v123, 0xffff0000, v123
	v_add_f32_e32 v52, 1.0, v52
	v_add_f32_e32 v53, 1.0, v53
	v_mul_f32_e32 v44, 0xbfb8aa3b, v44
	v_mul_f32_e32 v45, 0xbfb8aa3b, v45
	v_lshlrev_b64 v[134:135], 14, v[134:135]
	v_pk_fma_f32 v[62:63], v[62:63], v[122:123], v[118:119]
	v_lshlrev_b32_e32 v118, 16, v120
	v_and_b32_e32 v119, 0xffff0000, v120
	v_lshlrev_b32_e32 v122, 16, v124
	v_and_b32_e32 v123, 0xffff0000, v124
	v_rcp_f32_e32 v52, v52
	v_rcp_f32_e32 v53, v53
	v_add_f32_e32 v54, 1.0, v54
	v_add_f32_e32 v55, 1.0, v55
	v_exp_f32_e32 v44, v44
	v_exp_f32_e32 v45, v45
	v_mul_f32_e32 v46, 0xbfb8aa3b, v46
	v_mul_f32_e32 v47, 0xbfb8aa3b, v47
	v_lshl_add_u64 v[134:135], s[4:5], 0, v[134:135]
	v_pk_fma_f32 v[56:57], v[56:57], v[122:123], v[118:119]
	v_lshlrev_b32_e32 v118, 16, v121
	v_and_b32_e32 v119, 0xffff0000, v121
	v_lshlrev_b32_e32 v120, 16, v125
	v_and_b32_e32 v121, 0xffff0000, v125
	v_rcp_f32_e32 v54, v54
	v_rcp_f32_e32 v55, v55
	v_add_f32_e32 v48, 1.0, v48
	v_add_f32_e32 v49, 1.0, v49
	v_exp_f32_e32 v46, v46
	v_exp_f32_e32 v47, v47
	v_mul_f32_e32 v40, 0xbfb8aa3b, v40
	v_mul_f32_e32 v41, 0xbfb8aa3b, v41
	v_lshl_add_u64 v[134:135], v[134:135], 0, v[188:189]
	v_add_f32_e32 v60, 1.0, v60
	v_add_f32_e32 v61, 1.0, v61
	v_pk_fma_f32 v[58:59], v[58:59], v[120:121], v[118:119]
	v_rcp_f32_e32 v48, v48
	v_rcp_f32_e32 v49, v49
	v_add_f32_e32 v50, 1.0, v50
	v_add_f32_e32 v51, 1.0, v51
	v_exp_f32_e32 v40, v40
	v_exp_f32_e32 v41, v41
	v_mul_f32_e32 v42, 0xbfb8aa3b, v42
	v_mul_f32_e32 v43, 0xbfb8aa3b, v43
	v_rcp_f32_e32 v60, v60
	v_rcp_f32_e32 v61, v61
	global_store_dwordx4 v[134:135], v[56:59], off offset:16
	v_rcp_f32_e32 v50, v50
	v_rcp_f32_e32 v51, v51
	v_lshlrev_b32_e32 v56, 16, v130
	v_and_b32_e32 v57, 0xffff0000, v130
	v_lshlrev_b32_e32 v58, 16, v126
	v_and_b32_e32 v59, 0xffff0000, v126
	v_exp_f32_e32 v42, v42
	v_exp_f32_e32 v43, v43
	v_pk_fma_f32 v[52:53], v[52:53], v[58:59], v[56:57]
	v_lshlrev_b32_e32 v56, 16, v131
	v_and_b32_e32 v57, 0xffff0000, v131
	v_lshlrev_b32_e32 v58, 16, v127
	v_and_b32_e32 v59, 0xffff0000, v127
	v_add_f32_e32 v44, 1.0, v44
	v_add_f32_e32 v45, 1.0, v45
	v_mul_f32_e32 v36, 0xbfb8aa3b, v36
	v_mul_f32_e32 v37, 0xbfb8aa3b, v37
	v_pk_fma_f32 v[54:55], v[54:55], v[58:59], v[56:57]
	v_lshlrev_b32_e32 v56, 16, v132
	v_and_b32_e32 v57, 0xffff0000, v132
	v_lshlrev_b32_e32 v58, 16, v128
	v_and_b32_e32 v59, 0xffff0000, v128
	v_rcp_f32_e32 v44, v44
	v_rcp_f32_e32 v45, v45
	v_add_f32_e32 v46, 1.0, v46
	v_add_f32_e32 v47, 1.0, v47
	v_exp_f32_e32 v36, v36
	v_exp_f32_e32 v37, v37
	v_mul_f32_e32 v38, 0xbfb8aa3b, v38
	v_mul_f32_e32 v39, 0xbfb8aa3b, v39
	v_pk_fma_f32 v[48:49], v[48:49], v[58:59], v[56:57]
	v_lshlrev_b32_e32 v56, 16, v133
	v_and_b32_e32 v57, 0xffff0000, v133
	v_lshlrev_b32_e32 v58, 16, v129
	v_and_b32_e32 v59, 0xffff0000, v129
	v_rcp_f32_e32 v46, v46
	v_rcp_f32_e32 v47, v47
	v_add_f32_e32 v40, 1.0, v40
	v_add_f32_e32 v41, 1.0, v41
	v_exp_f32_e32 v38, v38
	v_exp_f32_e32 v39, v39
	v_mul_f32_e32 v32, 0xbfb8aa3b, v32
	v_mul_f32_e32 v33, 0xbfb8aa3b, v33
	v_pk_fma_f32 v[60:61], v[60:61], v[138:139], v[136:137]
	v_pk_fma_f32 v[50:51], v[50:51], v[58:59], v[56:57]
	v_rcp_f32_e32 v40, v40
	v_rcp_f32_e32 v41, v41
	v_add_f32_e32 v42, 1.0, v42
	v_add_f32_e32 v43, 1.0, v43
	v_exp_f32_e32 v32, v32
	v_exp_f32_e32 v33, v33
	v_mul_f32_e32 v34, 0xbfb8aa3b, v34
	v_mul_f32_e32 v35, 0xbfb8aa3b, v35
	global_store_dwordx4 v[134:135], v[60:63], off
	global_store_dwordx4 v[134:135], v[52:55], off offset:512
	global_store_dwordx4 v[134:135], v[48:51], off offset:528
	v_rcp_f32_e32 v42, v42
	v_lshlrev_b32_e32 v52, 16, v104
	v_lshlrev_b32_e32 v50, 16, v108
	v_and_b32_e32 v51, 0xffff0000, v108
	v_and_b32_e32 v53, 0xffff0000, v104
	v_rcp_f32_e32 v43, v43
	v_exp_f32_e32 v34, v34
	v_exp_f32_e32 v35, v35
	v_pk_fma_f32 v[44:45], v[44:45], v[52:53], v[50:51]
	v_lshlrev_b32_e32 v50, 16, v109
	v_and_b32_e32 v51, 0xffff0000, v109
	v_lshlrev_b32_e32 v52, 16, v105
	v_and_b32_e32 v53, 0xffff0000, v105
	v_add_f32_e32 v36, 1.0, v36
	v_add_f32_e32 v37, 1.0, v37
	v_mul_f32_e32 v28, 0xbfb8aa3b, v28
	v_mul_f32_e32 v29, 0xbfb8aa3b, v29
	v_lshlrev_b64 v[48:49], 14, v[116:117]
	v_pk_fma_f32 v[46:47], v[46:47], v[52:53], v[50:51]
	v_lshlrev_b32_e32 v50, 16, v110
	v_and_b32_e32 v51, 0xffff0000, v110
	v_lshlrev_b32_e32 v52, 16, v106
	v_and_b32_e32 v53, 0xffff0000, v106
	v_rcp_f32_e32 v36, v36
	v_rcp_f32_e32 v37, v37
	v_add_f32_e32 v38, 1.0, v38
	v_add_f32_e32 v39, 1.0, v39
	v_exp_f32_e32 v28, v28
	v_exp_f32_e32 v29, v29
	v_mul_f32_e32 v30, 0xbfb8aa3b, v30
	v_mul_f32_e32 v31, 0xbfb8aa3b, v31
	v_lshl_add_u64 v[48:49], s[4:5], 0, v[48:49]
	v_pk_fma_f32 v[40:41], v[40:41], v[52:53], v[50:51]
	v_lshlrev_b32_e32 v50, 16, v111
	v_and_b32_e32 v51, 0xffff0000, v111
	v_lshlrev_b32_e32 v52, 16, v107
	v_and_b32_e32 v53, 0xffff0000, v107
	v_rcp_f32_e32 v38, v38
	v_rcp_f32_e32 v39, v39
	v_add_f32_e32 v32, 1.0, v32
	v_add_f32_e32 v33, 1.0, v33
	v_exp_f32_e32 v30, v30
	v_exp_f32_e32 v31, v31
	v_mul_f32_e32 v24, 0xbfb8aa3b, v24
	v_mul_f32_e32 v25, 0xbfb8aa3b, v25
	v_lshl_add_u64 v[48:49], v[48:49], 0, v[188:189]
	v_pk_fma_f32 v[42:43], v[42:43], v[52:53], v[50:51]
	v_rcp_f32_e32 v32, v32
	v_rcp_f32_e32 v33, v33
	v_add_f32_e32 v34, 1.0, v34
	v_add_f32_e32 v35, 1.0, v35
	v_exp_f32_e32 v24, v24
	v_exp_f32_e32 v25, v25
	v_mul_f32_e32 v26, 0xbfb8aa3b, v26
	v_mul_f32_e32 v27, 0xbfb8aa3b, v27
	global_store_dwordx4 v[48:49], v[40:43], off offset:16
; DI float bflo(unsigned u) { return __uint_as_float(u << 16); }
; DI float bfhi(unsigned u) { return __uint_as_float(u & 0xffff0000u); }
; DI float sigmoidf_(float v) { return fast_rcp(1.0f + fast_exp2(-v * LOG2E)); }
;     DI void operator()(AccRef acc, const Unit& u, int wr, int wc, int fr, int fq) const {
;     ...
;             for (int m = 0; m < 4; ++m)
; #pragma unroll
;                 for (int bj = 0; bj < 2; ++bj) {
;                     float* op = out + (size_t)(row0 + ai * 128 + m * 16) * D + col0 + bj * 128;
;                     const u32x4 p4 = pv[m][bj], x4 = xv[m][bj];
;                     const f32x4 a0 = acc[ai][bj][m][0], a1 = acc[ai][bj][m][1];
;                     f32x4 x0, x1;
;                     x0[0] = bflo(x4.x) + sigmoidf_(a0[0]) * bflo(p4.x); x0[1] = bfhi(x4.x) + sigmoidf_(a0[1]) * bfhi(p4.x);
;                     x0[2] = bflo(x4.y) + sigmoidf_(a0[2]) * bflo(p4.y); x0[3] = bfhi(x4.y) + sigmoidf_(a0[3]) * bfhi(p4.y);
;                     x1[0] = bflo(x4.z) + sigmoidf_(a1[0]) * bflo(p4.z); x1[1] = bfhi(x4.z) + sigmoidf_(a1[1]) * bfhi(p4.z);
;                     x1[2] = bflo(x4.w) + sigmoidf_(a1[2]) * bflo(p4.w); x1[3] = bfhi(x4.w) + sigmoidf_(a1[3]) * bfhi(p4.w);
;                     *(f32x4*)op = x0; *(f32x4*)(op + 4) = x1;
	v_rcp_f32_e32 v34, v34
	v_rcp_f32_e32 v35, v35
	v_lshlrev_b32_e32 v40, 16, v100
	v_and_b32_e32 v41, 0xffff0000, v100
	v_lshlrev_b32_e32 v42, 16, v96
	v_and_b32_e32 v43, 0xffff0000, v96
	v_exp_f32_e32 v26, v26
	v_exp_f32_e32 v27, v27
	v_pk_fma_f32 v[36:37], v[36:37], v[42:43], v[40:41]
	v_lshlrev_b32_e32 v40, 16, v101
	v_and_b32_e32 v41, 0xffff0000, v101
	v_lshlrev_b32_e32 v42, 16, v97
	v_and_b32_e32 v43, 0xffff0000, v97
	v_add_f32_e32 v28, 1.0, v28
	v_add_f32_e32 v29, 1.0, v29
	v_mul_f32_e32 v20, 0xbfb8aa3b, v20
	v_mul_f32_e32 v21, 0xbfb8aa3b, v21
	v_pk_fma_f32 v[38:39], v[38:39], v[42:43], v[40:41]
	v_lshlrev_b32_e32 v40, 16, v102
	v_and_b32_e32 v41, 0xffff0000, v102
	v_lshlrev_b32_e32 v42, 16, v98
	v_and_b32_e32 v43, 0xffff0000, v98
	v_rcp_f32_e32 v28, v28
	v_rcp_f32_e32 v29, v29
	v_add_f32_e32 v30, 1.0, v30
	v_add_f32_e32 v31, 1.0, v31
	v_exp_f32_e32 v20, v20
	v_exp_f32_e32 v21, v21
	v_mul_f32_e32 v22, 0xbfb8aa3b, v22
	v_mul_f32_e32 v23, 0xbfb8aa3b, v23
	v_pk_fma_f32 v[32:33], v[32:33], v[42:43], v[40:41]
	v_lshlrev_b32_e32 v40, 16, v103
	v_and_b32_e32 v41, 0xffff0000, v103
	v_lshlrev_b32_e32 v42, 16, v99
	v_and_b32_e32 v43, 0xffff0000, v99
	v_rcp_f32_e32 v30, v30
	v_rcp_f32_e32 v31, v31
	v_add_f32_e32 v24, 1.0, v24
	v_add_f32_e32 v25, 1.0, v25
	v_exp_f32_e32 v22, v22
	v_exp_f32_e32 v23, v23
	v_mul_f32_e32 v16, 0xbfb8aa3b, v16
	v_mul_f32_e32 v17, 0xbfb8aa3b, v17
	v_pk_fma_f32 v[34:35], v[34:35], v[42:43], v[40:41]
	v_rcp_f32_e32 v24, v24
	v_rcp_f32_e32 v25, v25
	v_add_f32_e32 v26, 1.0, v26
	v_add_f32_e32 v27, 1.0, v27
	v_exp_f32_e32 v16, v16
	v_exp_f32_e32 v17, v17
	v_mul_f32_e32 v18, 0xbfb8aa3b, v18
	v_mul_f32_e32 v19, 0xbfb8aa3b, v19
	global_store_dwordx4 v[48:49], v[44:47], off
	global_store_dwordx4 v[48:49], v[36:39], off offset:512
	global_store_dwordx4 v[48:49], v[32:35], off offset:528
	v_rcp_f32_e32 v26, v26
	v_lshlrev_b32_e32 v36, 16, v88
	v_lshlrev_b32_e32 v34, 16, v92
	v_and_b32_e32 v35, 0xffff0000, v92
	v_and_b32_e32 v37, 0xffff0000, v88
	v_rcp_f32_e32 v27, v27
	v_exp_f32_e32 v18, v18
	v_exp_f32_e32 v19, v19
	v_pk_fma_f32 v[28:29], v[28:29], v[36:37], v[34:35]
	v_lshlrev_b32_e32 v34, 16, v93
	v_and_b32_e32 v35, 0xffff0000, v93
	v_lshlrev_b32_e32 v36, 16, v89
	v_and_b32_e32 v37, 0xffff0000, v89
	v_add_f32_e32 v20, 1.0, v20
	v_add_f32_e32 v21, 1.0, v21
	v_mul_f32_e32 v12, 0xbfb8aa3b, v12
	v_mul_f32_e32 v13, 0xbfb8aa3b, v13
	v_lshlrev_b64 v[32:33], 14, v[114:115]
	v_pk_fma_f32 v[30:31], v[30:31], v[36:37], v[34:35]
	v_lshlrev_b32_e32 v34, 16, v94
	v_and_b32_e32 v35, 0xffff0000, v94
	v_lshlrev_b32_e32 v36, 16, v90
	v_and_b32_e32 v37, 0xffff0000, v90
	v_rcp_f32_e32 v20, v20
	v_rcp_f32_e32 v21, v21
	v_add_f32_e32 v22, 1.0, v22
	v_add_f32_e32 v23, 1.0, v23
	v_exp_f32_e32 v12, v12
	v_exp_f32_e32 v13, v13
	v_mul_f32_e32 v14, 0xbfb8aa3b, v14
	v_mul_f32_e32 v15, 0xbfb8aa3b, v15
	v_lshl_add_u64 v[32:33], s[4:5], 0, v[32:33]
	v_pk_fma_f32 v[24:25], v[24:25], v[36:37], v[34:35]
	v_lshlrev_b32_e32 v34, 16, v95
	v_and_b32_e32 v35, 0xffff0000, v95
	v_lshlrev_b32_e32 v36, 16, v91
	v_and_b32_e32 v37, 0xffff0000, v91
	v_rcp_f32_e32 v22, v22
	v_rcp_f32_e32 v23, v23
	v_add_f32_e32 v16, 1.0, v16
	v_add_f32_e32 v17, 1.0, v17
	v_exp_f32_e32 v14, v14
	v_exp_f32_e32 v15, v15
	v_mul_f32_e32 v8, 0xbfb8aa3b, v8
	v_mul_f32_e32 v9, 0xbfb8aa3b, v9
	v_lshl_add_u64 v[32:33], v[32:33], 0, v[188:189]
	v_pk_fma_f32 v[26:27], v[26:27], v[36:37], v[34:35]
	v_rcp_f32_e32 v16, v16
	v_rcp_f32_e32 v17, v17
	v_add_f32_e32 v18, 1.0, v18
	v_add_f32_e32 v19, 1.0, v19
	v_exp_f32_e32 v8, v8
	v_exp_f32_e32 v9, v9
	v_mul_f32_e32 v10, 0xbfb8aa3b, v10
	v_mul_f32_e32 v11, 0xbfb8aa3b, v11
	global_store_dwordx4 v[32:33], v[24:27], off offset:16
	v_rcp_f32_e32 v18, v18
	v_rcp_f32_e32 v19, v19
	v_lshlrev_b32_e32 v24, 16, v84
	v_and_b32_e32 v25, 0xffff0000, v84
	v_lshlrev_b32_e32 v26, 16, v80
	v_and_b32_e32 v27, 0xffff0000, v80
	v_exp_f32_e32 v10, v10
	v_exp_f32_e32 v11, v11
	v_pk_fma_f32 v[20:21], v[20:21], v[26:27], v[24:25]
; DI float bflo(unsigned u) { return __uint_as_float(u << 16); }
; DI float bfhi(unsigned u) { return __uint_as_float(u & 0xffff0000u); }
; DI float sigmoidf_(float v) { return fast_rcp(1.0f + fast_exp2(-v * LOG2E)); }
; #define PG8_BAR __builtin_amdgcn_s_barrier()
; template <class Epi>
; DI void gemm_phase(LAS unsigned char* lds, const Gemm g, const StaticOrder& S, const Epi& E) {
;     ...
;         if (wr == 0) PG8_BAR;
;         bool keep = false;
;         if constexpr (Epi::MIDK) { if (cur.half == 0) { E.mid(acc, cur, wr, wc, fr, fq); keep = true; } else E(acc, cur, wr, wc, fr, fq); } else E(acc, cur, wr, wc, fr, fq);
;         if (!has_next) break;
;         if (!keep)
; #pragma unroll
;         for (int a = 0; a < 2; ++a)
; #pragma unroll
;             for (int b = 0; b < 2; ++b)
; #pragma unroll
;                 for (int m = 0; m < 4; ++m)
; #pragma unroll
;                     for (int n = 0; n < 2; ++n) acc[a][b][m][n] = (f32x4){0.f, 0.f, 0.f, 0.f};
;         cur = nxt; cA = nA; cB = nB; ++ui;
;         if (wr == 1) PG8_BAR;
;     DI void operator()(AccRef acc, const Unit& u, int wr, int wc, int fr, int fq) const {
;     ...
;             for (int m = 0; m < 4; ++m)
; #pragma unroll
;                 for (int bj = 0; bj < 2; ++bj) {
;                     float* op = out + (size_t)(row0 + ai * 128 + m * 16) * D + col0 + bj * 128;
;                     const u32x4 p4 = pv[m][bj], x4 = xv[m][bj];
;                     const f32x4 a0 = acc[ai][bj][m][0], a1 = acc[ai][bj][m][1];
;                     f32x4 x0, x1;
;                     x0[0] = bflo(x4.x) + sigmoidf_(a0[0]) * bflo(p4.x); x0[1] = bfhi(x4.x) + sigmoidf_(a0[1]) * bfhi(p4.x);
;                     x0[2] = bflo(x4.y) + sigmoidf_(a0[2]) * bflo(p4.y); x0[3] = bfhi(x4.y) + sigmoidf_(a0[3]) * bfhi(p4.y);
;                     x1[0] = bflo(x4.z) + sigmoidf_(a1[0]) * bflo(p4.z); x1[1] = bfhi(x4.z) + sigmoidf_(a1[1]) * bfhi(p4.z);
;                     x1[2] = bflo(x4.w) + sigmoidf_(a1[2]) * bflo(p4.w); x1[3] = bfhi(x4.w) + sigmoidf_(a1[3]) * bfhi(p4.w);
;                     *(f32x4*)op = x0; *(f32x4*)(op + 4) = x1;
	v_lshlrev_b32_e32 v24, 16, v85
	v_and_b32_e32 v25, 0xffff0000, v85
	v_lshlrev_b32_e32 v26, 16, v81
	v_and_b32_e32 v27, 0xffff0000, v81
	v_add_f32_e32 v12, 1.0, v12
	v_add_f32_e32 v13, 1.0, v13
	v_mul_f32_e32 v4, 0xbfb8aa3b, v4
	v_mul_f32_e32 v5, 0xbfb8aa3b, v5
	v_pk_fma_f32 v[22:23], v[22:23], v[26:27], v[24:25]
	v_lshlrev_b32_e32 v24, 16, v86
	v_and_b32_e32 v25, 0xffff0000, v86
	v_lshlrev_b32_e32 v26, 16, v82
	v_and_b32_e32 v27, 0xffff0000, v82
	v_rcp_f32_e32 v12, v12
	v_rcp_f32_e32 v13, v13
	v_add_f32_e32 v14, 1.0, v14
	v_add_f32_e32 v15, 1.0, v15
	v_exp_f32_e32 v4, v4
	v_exp_f32_e32 v5, v5
	v_mul_f32_e32 v6, 0xbfb8aa3b, v6
	v_mul_f32_e32 v7, 0xbfb8aa3b, v7
	v_pk_fma_f32 v[16:17], v[16:17], v[26:27], v[24:25]
	v_lshlrev_b32_e32 v24, 16, v87
	v_and_b32_e32 v25, 0xffff0000, v87
	v_lshlrev_b32_e32 v26, 16, v83
	v_and_b32_e32 v27, 0xffff0000, v83
	v_rcp_f32_e32 v14, v14
	v_rcp_f32_e32 v15, v15
	v_add_f32_e32 v8, 1.0, v8
	v_add_f32_e32 v9, 1.0, v9
	v_exp_f32_e32 v6, v6
	v_exp_f32_e32 v7, v7
	v_mul_f32_e32 v0, 0xbfb8aa3b, v0
	v_mul_f32_e32 v1, 0xbfb8aa3b, v1
	v_pk_fma_f32 v[18:19], v[18:19], v[26:27], v[24:25]
	v_rcp_f32_e32 v8, v8
	v_rcp_f32_e32 v9, v9
	v_add_f32_e32 v10, 1.0, v10
	v_add_f32_e32 v11, 1.0, v11
	v_exp_f32_e32 v0, v0
	v_exp_f32_e32 v1, v1
	v_mul_f32_e32 v2, 0xbfb8aa3b, v2
	v_mul_f32_e32 v3, 0xbfb8aa3b, v3
	global_store_dwordx4 v[32:33], v[28:31], off
	global_store_dwordx4 v[32:33], v[20:23], off offset:512
	global_store_dwordx4 v[32:33], v[16:19], off offset:528
	v_rcp_f32_e32 v10, v10
	v_lshlrev_b32_e32 v20, 16, v72
	v_lshlrev_b32_e32 v18, 16, v76
	v_and_b32_e32 v19, 0xffff0000, v76
	v_and_b32_e32 v21, 0xffff0000, v72
	v_rcp_f32_e32 v11, v11
	v_exp_f32_e32 v2, v2
	v_exp_f32_e32 v3, v3
	v_pk_fma_f32 v[12:13], v[12:13], v[20:21], v[18:19]
	v_lshlrev_b32_e32 v18, 16, v77
	v_and_b32_e32 v19, 0xffff0000, v77
	v_lshlrev_b32_e32 v20, 16, v73
	v_and_b32_e32 v21, 0xffff0000, v73
	v_add_f32_e32 v4, 1.0, v4
	v_add_f32_e32 v5, 1.0, v5
	v_lshlrev_b64 v[16:17], 14, v[112:113]
	v_pk_fma_f32 v[14:15], v[14:15], v[20:21], v[18:19]
	v_lshlrev_b32_e32 v18, 16, v78
	v_and_b32_e32 v19, 0xffff0000, v78
	v_lshlrev_b32_e32 v20, 16, v74
	v_and_b32_e32 v21, 0xffff0000, v74
	v_rcp_f32_e32 v4, v4
	v_rcp_f32_e32 v5, v5
	v_add_f32_e32 v6, 1.0, v6
	v_add_f32_e32 v7, 1.0, v7
	v_lshl_add_u64 v[16:17], s[4:5], 0, v[16:17]
	v_pk_fma_f32 v[8:9], v[8:9], v[20:21], v[18:19]
	v_lshlrev_b32_e32 v18, 16, v79
	v_and_b32_e32 v19, 0xffff0000, v79
	v_lshlrev_b32_e32 v20, 16, v75
	v_and_b32_e32 v21, 0xffff0000, v75
	v_rcp_f32_e32 v6, v6
	v_rcp_f32_e32 v7, v7
	v_add_f32_e32 v0, 1.0, v0
	v_add_f32_e32 v1, 1.0, v1
	v_lshl_add_u64 v[16:17], v[16:17], 0, v[188:189]
	v_pk_fma_f32 v[10:11], v[10:11], v[20:21], v[18:19]
	v_rcp_f32_e32 v0, v0
	v_rcp_f32_e32 v1, v1
	v_add_f32_e32 v2, 1.0, v2
	v_add_f32_e32 v3, 1.0, v3
	global_store_dwordx4 v[16:17], v[8:11], off offset:16
	v_rcp_f32_e32 v2, v2
	v_rcp_f32_e32 v3, v3
	v_lshlrev_b32_e32 v8, 16, v68
	v_and_b32_e32 v9, 0xffff0000, v68
	v_lshlrev_b32_e32 v10, 16, v64
	v_and_b32_e32 v11, 0xffff0000, v64
	v_pk_fma_f32 v[4:5], v[4:5], v[10:11], v[8:9]
	v_lshlrev_b32_e32 v8, 16, v69
	v_and_b32_e32 v9, 0xffff0000, v69
	v_lshlrev_b32_e32 v10, 16, v65
	v_and_b32_e32 v11, 0xffff0000, v65
	v_pk_fma_f32 v[6:7], v[6:7], v[10:11], v[8:9]
	v_lshlrev_b32_e32 v8, 16, v70
	v_and_b32_e32 v9, 0xffff0000, v70
	v_lshlrev_b32_e32 v10, 16, v66
	v_and_b32_e32 v11, 0xffff0000, v66
	v_pk_fma_f32 v[0:1], v[0:1], v[10:11], v[8:9]
	v_lshlrev_b32_e32 v8, 16, v71
	v_and_b32_e32 v9, 0xffff0000, v71
	v_lshlrev_b32_e32 v10, 16, v67
	v_and_b32_e32 v11, 0xffff0000, v67
	s_andn2_b64 vcc, exec, s[0:1]
	s_mov_b64 s[0:1], -1
	global_store_dwordx4 v[16:17], v[12:15], off
	v_pk_fma_f32 v[2:3], v[2:3], v[10:11], v[8:9]
	global_store_dwordx4 v[16:17], v[4:7], off offset:512
	global_store_dwordx4 v[16:17], v[0:3], off offset:528
	s_cbranch_vccnz .LBB0_963
	s_andn2_b64 vcc, exec, s[10:11]
	s_cbranch_vccnz .LBB0_962
	s_barrier
	s_branch .LBB0_962

; __global__ void __launch_bounds__(512, 2) mk_fwd(Params prm) {
	.amdhsa_kernel _Z6mk_fwd6Params
		.amdhsa_group_segment_fixed_size 0
		.amdhsa_private_segment_fixed_size 0
		.amdhsa_kernarg_size 448
		.amdhsa_user_sgpr_count 2
		.amdhsa_user_sgpr_dispatch_ptr 0
		.amdhsa_user_sgpr_queue_ptr 0
		.amdhsa_user_sgpr_kernarg_segment_ptr 1
		.amdhsa_user_sgpr_dispatch_id 0
		.amdhsa_user_sgpr_kernarg_preload_length 0
		.amdhsa_user_sgpr_kernarg_preload_offset 0
		.amdhsa_user_sgpr_private_segment_size 0
		.amdhsa_uses_dynamic_stack 0
		.amdhsa_enable_private_segment 0
		.amdhsa_system_sgpr_workgroup_id_x 1
		.amdhsa_system_sgpr_workgroup_id_y 0
		.amdhsa_system_sgpr_workgroup_id_z 0
		.amdhsa_system_sgpr_workgroup_info 0
		.amdhsa_system_vgpr_workitem_id 2
		.amdhsa_next_free_vgpr 254
		.amdhsa_next_free_sgpr 96
		.amdhsa_accum_offset 256
		.amdhsa_reserve_vcc 1
		.amdhsa_float_round_mode_32 0
		.amdhsa_float_round_mode_16_64 0
		.amdhsa_float_denorm_mode_32 3
		.amdhsa_float_denorm_mode_16_64 3
		.amdhsa_dx10_clamp 1
		.amdhsa_ieee_mode 1
		.amdhsa_fp16_overflow 0
		.amdhsa_tg_split 0
		.amdhsa_exception_fp_ieee_invalid_op 0
		.amdhsa_exception_fp_denorm_src 0
		.amdhsa_exception_fp_ieee_div_zero 0
		.amdhsa_exception_fp_ieee_overflow 0
		.amdhsa_exception_fp_ieee_underflow 0
		.amdhsa_exception_fp_ieee_inexact 0
		.amdhsa_exception_int_div_zero 0
	.end_amdhsa_kernel

; __global__ void __launch_bounds__(512, 2) mk_fwd(Params prm) {
amdhsa.kernels:
  - .agpr_count:     0
    .args:
      - .offset:         0
        .size:           192
        .value_kind:     by_value
      - .offset:         192
        .size:           4
        .value_kind:     hidden_block_count_x
      - .offset:         196
        .size:           4
        .value_kind:     hidden_block_count_y
      - .offset:         200
        .size:           4
        .value_kind:     hidden_block_count_z
      - .offset:         204
        .size:           2
        .value_kind:     hidden_group_size_x
      - .offset:         206
        .size:           2
        .value_kind:     hidden_group_size_y
      - .offset:         208
        .size:           2
        .value_kind:     hidden_group_size_z
      - .offset:         210
        .size:           2
        .value_kind:     hidden_remainder_x
      - .offset:         212
        .size:           2
        .value_kind:     hidden_remainder_y
      - .offset:         214
        .size:           2
        .value_kind:     hidden_remainder_z
      - .offset:         232
        .size:           8
        .value_kind:     hidden_global_offset_x
      - .offset:         240
        .size:           8
        .value_kind:     hidden_global_offset_y
      - .offset:         248
        .size:           8
        .value_kind:     hidden_global_offset_z
      - .offset:         256
        .size:           2
        .value_kind:     hidden_grid_dims
      - .offset:         280
        .size:           8
        .value_kind:     hidden_multigrid_sync_arg
      - .offset:         312
        .size:           4
        .value_kind:     hidden_dynamic_lds_size
    .group_segment_fixed_size: 0
    .kernarg_segment_align: 8
    .kernarg_segment_size: 448
    .language:       OpenCL C
    .language_version:
      - 2
      - 0
    .max_flat_workgroup_size: 512
    .name:           _Z6mk_fwd6Params
    .private_segment_fixed_size: 0
    .sgpr_count:     102
    .sgpr_spill_count: 0
    .symbol:         _Z6mk_fwd6Params.kd
    .uniform_work_group_size: 1
    .uses_dynamic_stack: false
    .vgpr_count:     254
    .vgpr_spill_count: 0
    .wavefront_size: 64
